# prologue silu(c) table: all 18 per-thread loads issued together instead of load-wait per iteration
# speedup vs baseline: 1.0052x; 1.0052x over previous
.LBB0_1063:
	s_andn2_b64 vcc, exec, s[24:25]
	s_cbranch_vccnz .LBB0_1177
	s_movk_i32 s0, 0x2400
	v_cmp_gt_i32_e32 vcc, s0, v182
	s_and_saveexec_b64 s[24:25], vcc
	s_cbranch_execz .LBB0_1067
	v_ashrrev_i32_e32 v183, 31, v182
	s_waitcnt vmcnt(0) lgkmcnt(0)
	v_lshlrev_b32_e32 v2, 2, v182
	s_mov_b32 s98, s82
	s_mov_b32 s99, s83
	global_load_dword v10, v2, s[98:99]
	global_load_dword v11, v2, s[98:99] offset:2048
	s_add_u32 s98, s98, 0x1000
	s_addc_u32 s99, s99, 0
	global_load_dword v12, v2, s[98:99]
	global_load_dword v13, v2, s[98:99] offset:2048
	s_add_u32 s98, s98, 0x1000
	s_addc_u32 s99, s99, 0
	global_load_dword v14, v2, s[98:99]
	global_load_dword v15, v2, s[98:99] offset:2048
	s_add_u32 s98, s98, 0x1000
	s_addc_u32 s99, s99, 0
	global_load_dword v16, v2, s[98:99]
	global_load_dword v17, v2, s[98:99] offset:2048
	s_add_u32 s98, s98, 0x1000
	s_addc_u32 s99, s99, 0
	global_load_dword v18, v2, s[98:99]
	global_load_dword v19, v2, s[98:99] offset:2048
	s_add_u32 s98, s98, 0x1000
	s_addc_u32 s99, s99, 0
	global_load_dword v20, v2, s[98:99]
	global_load_dword v21, v2, s[98:99] offset:2048
	s_add_u32 s98, s98, 0x1000
	s_addc_u32 s99, s99, 0
	global_load_dword v22, v2, s[98:99]
	global_load_dword v23, v2, s[98:99] offset:2048
	s_add_u32 s98, s98, 0x1000
	s_addc_u32 s99, s99, 0
	global_load_dword v24, v2, s[98:99]
	global_load_dword v25, v2, s[98:99] offset:2048
	global_load_dword v26, v2, s[86:87]
	global_load_dword v27, v2, s[86:87] offset:2048
	s_waitcnt vmcnt(0)
	v_mul_f32_e32 v5, 0xbfb8aa3b, v10
	v_exp_f32_e32 v5, v5
	s_nop 0
	v_add_f32_e32 v5, 1.0, v5
	v_div_scale_f32 v6, s[2:3], v5, v5, v10
	v_rcp_f32_e32 v7, v6
	v_div_scale_f32 v8, vcc, v10, v5, v10
	v_fma_f32 v9, -v6, v7, 1.0
	v_fmac_f32_e32 v7, v9, v7
	v_mul_f32_e32 v9, v8, v7
	v_fma_f32 v4, -v6, v9, v8
	v_fmac_f32_e32 v9, v4, v7
	v_fma_f32 v6, -v6, v9, v8
	v_div_fmas_f32 v6, v6, v7, v9
	v_div_fixup_f32 v4, v6, v5, v10
	ds_write_b32 v2, v4
	v_mul_f32_e32 v5, 0xbfb8aa3b, v11
	v_exp_f32_e32 v5, v5
	s_nop 0
	v_add_f32_e32 v5, 1.0, v5
	v_div_scale_f32 v6, s[2:3], v5, v5, v11
	v_rcp_f32_e32 v7, v6
	v_div_scale_f32 v8, vcc, v11, v5, v11
	v_fma_f32 v9, -v6, v7, 1.0
	v_fmac_f32_e32 v7, v9, v7
	v_mul_f32_e32 v9, v8, v7
	v_fma_f32 v4, -v6, v9, v8
	v_fmac_f32_e32 v9, v4, v7
	v_fma_f32 v6, -v6, v9, v8
	v_div_fmas_f32 v6, v6, v7, v9
	v_div_fixup_f32 v4, v6, v5, v11
	ds_write_b32 v2, v4 offset:2048
	v_mul_f32_e32 v5, 0xbfb8aa3b, v12
	v_exp_f32_e32 v5, v5
	s_nop 0
	v_add_f32_e32 v5, 1.0, v5
	v_div_scale_f32 v6, s[2:3], v5, v5, v12
	v_rcp_f32_e32 v7, v6
	v_div_scale_f32 v8, vcc, v12, v5, v12
	v_fma_f32 v9, -v6, v7, 1.0
	v_fmac_f32_e32 v7, v9, v7
	v_mul_f32_e32 v9, v8, v7
	v_fma_f32 v4, -v6, v9, v8
	v_fmac_f32_e32 v9, v4, v7
	v_fma_f32 v6, -v6, v9, v8
	v_div_fmas_f32 v6, v6, v7, v9
	v_div_fixup_f32 v4, v6, v5, v12
	ds_write_b32 v2, v4 offset:4096
	v_mul_f32_e32 v5, 0xbfb8aa3b, v13
	v_exp_f32_e32 v5, v5
	s_nop 0
	v_add_f32_e32 v5, 1.0, v5
	v_div_scale_f32 v6, s[2:3], v5, v5, v13
	v_rcp_f32_e32 v7, v6
	v_div_scale_f32 v8, vcc, v13, v5, v13
	v_fma_f32 v9, -v6, v7, 1.0
	v_fmac_f32_e32 v7, v9, v7
	v_mul_f32_e32 v9, v8, v7
	v_fma_f32 v4, -v6, v9, v8
	v_fmac_f32_e32 v9, v4, v7
	v_fma_f32 v6, -v6, v9, v8
	v_div_fmas_f32 v6, v6, v7, v9
	v_div_fixup_f32 v4, v6, v5, v13
	ds_write_b32 v2, v4 offset:6144
	v_mul_f32_e32 v5, 0xbfb8aa3b, v14
	v_exp_f32_e32 v5, v5
	s_nop 0
	v_add_f32_e32 v5, 1.0, v5
	v_div_scale_f32 v6, s[2:3], v5, v5, v14
	v_rcp_f32_e32 v7, v6
	v_div_scale_f32 v8, vcc, v14, v5, v14
	v_fma_f32 v9, -v6, v7, 1.0
	v_fmac_f32_e32 v7, v9, v7
	v_mul_f32_e32 v9, v8, v7
	v_fma_f32 v4, -v6, v9, v8
	v_fmac_f32_e32 v9, v4, v7
	v_fma_f32 v6, -v6, v9, v8
	v_div_fmas_f32 v6, v6, v7, v9
	v_div_fixup_f32 v4, v6, v5, v14
	ds_write_b32 v2, v4 offset:8192
	v_mul_f32_e32 v5, 0xbfb8aa3b, v15
	v_exp_f32_e32 v5, v5
	s_nop 0
	v_add_f32_e32 v5, 1.0, v5
	v_div_scale_f32 v6, s[2:3], v5, v5, v15
	v_rcp_f32_e32 v7, v6
	v_div_scale_f32 v8, vcc, v15, v5, v15
	v_fma_f32 v9, -v6, v7, 1.0
	v_fmac_f32_e32 v7, v9, v7
	v_mul_f32_e32 v9, v8, v7
	v_fma_f32 v4, -v6, v9, v8
	v_fmac_f32_e32 v9, v4, v7
	v_fma_f32 v6, -v6, v9, v8
	v_div_fmas_f32 v6, v6, v7, v9
	v_div_fixup_f32 v4, v6, v5, v15
	ds_write_b32 v2, v4 offset:10240
	v_mul_f32_e32 v5, 0xbfb8aa3b, v16
	v_exp_f32_e32 v5, v5
	s_nop 0
	v_add_f32_e32 v5, 1.0, v5
	v_div_scale_f32 v6, s[2:3], v5, v5, v16
	v_rcp_f32_e32 v7, v6
	v_div_scale_f32 v8, vcc, v16, v5, v16
	v_fma_f32 v9, -v6, v7, 1.0
	v_fmac_f32_e32 v7, v9, v7
	v_mul_f32_e32 v9, v8, v7
	v_fma_f32 v4, -v6, v9, v8
	v_fmac_f32_e32 v9, v4, v7
	v_fma_f32 v6, -v6, v9, v8
	v_div_fmas_f32 v6, v6, v7, v9
	v_div_fixup_f32 v4, v6, v5, v16
	ds_write_b32 v2, v4 offset:12288
	v_mul_f32_e32 v5, 0xbfb8aa3b, v17
	v_exp_f32_e32 v5, v5
	s_nop 0
	v_add_f32_e32 v5, 1.0, v5
	v_div_scale_f32 v6, s[2:3], v5, v5, v17
	v_rcp_f32_e32 v7, v6
	v_div_scale_f32 v8, vcc, v17, v5, v17
	v_fma_f32 v9, -v6, v7, 1.0
	v_fmac_f32_e32 v7, v9, v7
	v_mul_f32_e32 v9, v8, v7
	v_fma_f32 v4, -v6, v9, v8
	v_fmac_f32_e32 v9, v4, v7
	v_fma_f32 v6, -v6, v9, v8
	v_div_fmas_f32 v6, v6, v7, v9
	v_div_fixup_f32 v4, v6, v5, v17
	ds_write_b32 v2, v4 offset:14336
	v_mul_f32_e32 v5, 0xbfb8aa3b, v18
	v_exp_f32_e32 v5, v5
	s_nop 0
	v_add_f32_e32 v5, 1.0, v5
	v_div_scale_f32 v6, s[2:3], v5, v5, v18
	v_rcp_f32_e32 v7, v6
	v_div_scale_f32 v8, vcc, v18, v5, v18
	v_fma_f32 v9, -v6, v7, 1.0
	v_fmac_f32_e32 v7, v9, v7
	v_mul_f32_e32 v9, v8, v7
	v_fma_f32 v4, -v6, v9, v8
	v_fmac_f32_e32 v9, v4, v7
	v_fma_f32 v6, -v6, v9, v8
	v_div_fmas_f32 v6, v6, v7, v9
	v_div_fixup_f32 v4, v6, v5, v18
	ds_write_b32 v2, v4 offset:16384
	v_mul_f32_e32 v5, 0xbfb8aa3b, v19
	v_exp_f32_e32 v5, v5
	s_nop 0
	v_add_f32_e32 v5, 1.0, v5
	v_div_scale_f32 v6, s[2:3], v5, v5, v19
	v_rcp_f32_e32 v7, v6
	v_div_scale_f32 v8, vcc, v19, v5, v19
	v_fma_f32 v9, -v6, v7, 1.0
	v_fmac_f32_e32 v7, v9, v7
	v_mul_f32_e32 v9, v8, v7
	v_fma_f32 v4, -v6, v9, v8
	v_fmac_f32_e32 v9, v4, v7
	v_fma_f32 v6, -v6, v9, v8
	v_div_fmas_f32 v6, v6, v7, v9
	v_div_fixup_f32 v4, v6, v5, v19
	ds_write_b32 v2, v4 offset:18432
	v_mul_f32_e32 v5, 0xbfb8aa3b, v20
	v_exp_f32_e32 v5, v5
	s_nop 0
	v_add_f32_e32 v5, 1.0, v5
	v_div_scale_f32 v6, s[2:3], v5, v5, v20
	v_rcp_f32_e32 v7, v6
	v_div_scale_f32 v8, vcc, v20, v5, v20
	v_fma_f32 v9, -v6, v7, 1.0
	v_fmac_f32_e32 v7, v9, v7
	v_mul_f32_e32 v9, v8, v7
	v_fma_f32 v4, -v6, v9, v8
	v_fmac_f32_e32 v9, v4, v7
	v_fma_f32 v6, -v6, v9, v8
	v_div_fmas_f32 v6, v6, v7, v9
	v_div_fixup_f32 v4, v6, v5, v20
	ds_write_b32 v2, v4 offset:20480
	v_mul_f32_e32 v5, 0xbfb8aa3b, v21
	v_exp_f32_e32 v5, v5
	s_nop 0
	v_add_f32_e32 v5, 1.0, v5
	v_div_scale_f32 v6, s[2:3], v5, v5, v21
	v_rcp_f32_e32 v7, v6
	v_div_scale_f32 v8, vcc, v21, v5, v21
	v_fma_f32 v9, -v6, v7, 1.0
	v_fmac_f32_e32 v7, v9, v7
	v_mul_f32_e32 v9, v8, v7
	v_fma_f32 v4, -v6, v9, v8
	v_fmac_f32_e32 v9, v4, v7
	v_fma_f32 v6, -v6, v9, v8
	v_div_fmas_f32 v6, v6, v7, v9
	v_div_fixup_f32 v4, v6, v5, v21
	ds_write_b32 v2, v4 offset:22528
	v_mul_f32_e32 v5, 0xbfb8aa3b, v22
	v_exp_f32_e32 v5, v5
	s_nop 0
	v_add_f32_e32 v5, 1.0, v5
	v_div_scale_f32 v6, s[2:3], v5, v5, v22
	v_rcp_f32_e32 v7, v6
	v_div_scale_f32 v8, vcc, v22, v5, v22
	v_fma_f32 v9, -v6, v7, 1.0
	v_fmac_f32_e32 v7, v9, v7
	v_mul_f32_e32 v9, v8, v7
	v_fma_f32 v4, -v6, v9, v8
	v_fmac_f32_e32 v9, v4, v7
	v_fma_f32 v6, -v6, v9, v8
	v_div_fmas_f32 v6, v6, v7, v9
	v_div_fixup_f32 v4, v6, v5, v22
	ds_write_b32 v2, v4 offset:24576
	v_mul_f32_e32 v5, 0xbfb8aa3b, v23
	v_exp_f32_e32 v5, v5
	s_nop 0
	v_add_f32_e32 v5, 1.0, v5
	v_div_scale_f32 v6, s[2:3], v5, v5, v23
	v_rcp_f32_e32 v7, v6
	v_div_scale_f32 v8, vcc, v23, v5, v23
	v_fma_f32 v9, -v6, v7, 1.0
	v_fmac_f32_e32 v7, v9, v7
	v_mul_f32_e32 v9, v8, v7
	v_fma_f32 v4, -v6, v9, v8
	v_fmac_f32_e32 v9, v4, v7
	v_fma_f32 v6, -v6, v9, v8
	v_div_fmas_f32 v6, v6, v7, v9
	v_div_fixup_f32 v4, v6, v5, v23
	ds_write_b32 v2, v4 offset:26624
	v_mul_f32_e32 v5, 0xbfb8aa3b, v24
	v_exp_f32_e32 v5, v5
	s_nop 0
	v_add_f32_e32 v5, 1.0, v5
	v_div_scale_f32 v6, s[2:3], v5, v5, v24
	v_rcp_f32_e32 v7, v6
	v_div_scale_f32 v8, vcc, v24, v5, v24
	v_fma_f32 v9, -v6, v7, 1.0
	v_fmac_f32_e32 v7, v9, v7
	v_mul_f32_e32 v9, v8, v7
	v_fma_f32 v4, -v6, v9, v8
	v_fmac_f32_e32 v9, v4, v7
	v_fma_f32 v6, -v6, v9, v8
	v_div_fmas_f32 v6, v6, v7, v9
	v_div_fixup_f32 v4, v6, v5, v24
	ds_write_b32 v2, v4 offset:28672
	v_mul_f32_e32 v5, 0xbfb8aa3b, v25
	v_exp_f32_e32 v5, v5
	s_nop 0
	v_add_f32_e32 v5, 1.0, v5
	v_div_scale_f32 v6, s[2:3], v5, v5, v25
	v_rcp_f32_e32 v7, v6
	v_div_scale_f32 v8, vcc, v25, v5, v25
	v_fma_f32 v9, -v6, v7, 1.0
	v_fmac_f32_e32 v7, v9, v7
	v_mul_f32_e32 v9, v8, v7
	v_fma_f32 v4, -v6, v9, v8
	v_fmac_f32_e32 v9, v4, v7
	v_fma_f32 v6, -v6, v9, v8
	v_div_fmas_f32 v6, v6, v7, v9
	v_div_fixup_f32 v4, v6, v5, v25
	ds_write_b32 v2, v4 offset:30720
	v_mul_f32_e32 v5, 0xbfb8aa3b, v26
	v_exp_f32_e32 v5, v5
	s_nop 0
	v_add_f32_e32 v5, 1.0, v5
	v_div_scale_f32 v6, s[2:3], v5, v5, v26
	v_rcp_f32_e32 v7, v6
	v_div_scale_f32 v8, vcc, v26, v5, v26
	v_fma_f32 v9, -v6, v7, 1.0
	v_fmac_f32_e32 v7, v9, v7
	v_mul_f32_e32 v9, v8, v7
	v_fma_f32 v4, -v6, v9, v8
	v_fmac_f32_e32 v9, v4, v7
	v_fma_f32 v6, -v6, v9, v8
	v_div_fmas_f32 v6, v6, v7, v9
	v_div_fixup_f32 v4, v6, v5, v26
	ds_write_b32 v2, v4 offset:32768
	v_mul_f32_e32 v5, 0xbfb8aa3b, v27
	v_exp_f32_e32 v5, v5
	s_nop 0
	v_add_f32_e32 v5, 1.0, v5
	v_div_scale_f32 v6, s[2:3], v5, v5, v27
	v_rcp_f32_e32 v7, v6
	v_div_scale_f32 v8, vcc, v27, v5, v27
	v_fma_f32 v9, -v6, v7, 1.0
	v_fmac_f32_e32 v7, v9, v7
	v_mul_f32_e32 v9, v8, v7
	v_fma_f32 v4, -v6, v9, v8
	v_fmac_f32_e32 v9, v4, v7
	v_fma_f32 v6, -v6, v9, v8
	v_div_fmas_f32 v6, v6, v7, v9
	v_div_fixup_f32 v4, v6, v5, v27
	ds_write_b32 v2, v4 offset:34816
